# P2 K-loop: one 16-line touch load per iteration prefetches the f32 residual tile of the epilogue into L2/MALL (waits 9/9/9/8)
# baseline (speedup 1.0000x reference)
;     __device__ bool next(int i, pg8::Unit& u) const { const int L = i * G + c; if (L >= 64) return false; u.pm = L; u.pn = 0; u.aoff = (long)L * 256 * lda; u.boff = (long)(L >> 5) * 256 * ldb; return true; }
;     __device__ bool next(int i, Unit& u) const {
;         const long L = (long)i * G + c; if (L >= nwg) return false;
;         int wgid = (int)L; { const int q = nwg / NXCD, r = nwg % NXCD, xcd = wgid % NXCD, off = wgid / NXCD; wgid = (xcd < r ? xcd * (q + 1) : r * (q + 1) + (xcd - r) * q) + off; }
;         const int nig = WGM * nN, gid = wgid / nig, fm = gid * WGM, gsz = (nM - fm) < WGM ? (nM - fm) : WGM;
;         u.pm = fm + ((wgid % nig) % gsz); u.pn = (wgid % nig) / gsz;
;         u.aoff = (long)u.pm * BM * lda; u.boff = (long)u.pn * BM * ldb; return true;
.LBB0_1438:
	s_or_b64 exec, exec, s[0:1]
	v_mov_b32_e32 v8, v198
	v_and_b32_e32 v234, 15, v198
	v_lshrrev_b32_e32 v235, 3, v234
	v_and_b32_e32 v234, 7, v234
	v_lshlrev_b32_e32 v234, 7, v234
	v_lshl_or_b32 v234, v235, 12, v234
	v_lshrrev_b32_e32 v235, 6, v198
	v_lshl_or_b32 v234, v235, 17, v234
	v_mov_b32_e32 v235, 0
	s_cmpk_lt_i32 s88, 0x400
	s_waitcnt lgkmcnt(0)
	s_barrier
	s_cselect_b64 s[10:11], -1, 0
	s_cmpk_gt_i32 s88, 0x3ff
	v_readfirstlane_b32 s34, v8
	s_cbranch_scc1 .LBB0_1441
	s_ashr_i32 s0, s88, 31
	s_lshr_b32 s0, s0, 29
	s_add_i32 s6, s88, s0
	s_and_b32 s0, s6, -8
	s_sub_i32 s7, s88, s0
	s_cmp_gt_i32 s7, -1
	s_cbranch_scc0 .LBB0_1442
	s_lshl_b32 s8, s7, 7
	s_cbranch_execz .LBB0_1443
	s_branch .LBB0_1444

; #define PG8_STAGE(bufoff, gbase, voff) do { _Pragma("unroll") for (int _i = 0; _i < 2; ++_i) \
;         __builtin_amdgcn_global_load_lds((const unsigned*)((const char*)(gbase) + (voff)[_i]), (PG8_LAS unsigned*)(lds + (bufoff) + ldsw + _i * 8192), 16, 0, 0); } while (0)
; #define PG8_LDA(dst, b, h) do { _Pragma("unroll") for (int m = 0; m < 4; ++m) _Pragma("unroll") for (int k = 0; k < 2; ++k) dst[m][k] = *(const PG8_LAS bf16x8*)(lds + PG8_SA(b, h) + aoff + m * 2048 + k * 1024); } while (0)
; #define PG8_LDB(dst, b, h) do { _Pragma("unroll") for (int n = 0; n < 2; ++n) _Pragma("unroll") for (int k = 0; k < 2; ++k) dst[n][k] = *(const PG8_LAS bf16x8*)(lds + PG8_SB(b, h) + boff + n * 2048 + k * 1024); } while (0)
; #define PG8_WAIT_V(n) asm volatile("s_waitcnt vmcnt(" #n ")" ::: "memory")
; #define PG8_WAIT_L(n) asm volatile("s_waitcnt lgkmcnt(" #n ")" ::: "memory")
; #define PG8_BAR __builtin_amdgcn_s_barrier()
; #define PG8_SCHED __builtin_amdgcn_sched_barrier(0)
; template <class Epi, class Sched>
; __device__ __forceinline__ void gemm_phase(PG8_LAS unsigned char* lds, const Gemm g, const Sched& S, const Epi& E) {
;     ...
;         for (int t = 0; t < nt; t += 2) {
;             const bool last = (t == nt - 2);
;             const char* a1 = cA + (size_t)(t + 1) * kstepA;
;             const char* a2 = last ? nA : cA + (size_t)(t + 2) * kstepA; const char* b2 = last ? nB : cB + (size_t)(t + 2) * kstep;
;             const char* a3 = a2 + kstepA; const char* b3 = b2 + kstep;
;             if constexpr (epi_has_hook<Epi>::value) { if (t == nt / 2) E.hook(acc, cur, wr, wc, fr, fq); }
;             PG8_LDB(B0, 0, 0); PG8_LDB(B1, 0, 1); PG8_SCHED; PG8_LDA(At, 0, 0); PG8_STAGE(PG8_SA(1, 1), a1 + hstepA, voffA);
;             PG8_WAIT_V(8); PG8_WAIT_L(0); PG8_BAR; PG8_MMA(0, 0, At, B0); PG8_MMA(0, 1, At, B1); PG8_BAR; PG8_SCHED;
;             PG8_LDA(At, 0, 1); PG8_STAGE(PG8_SB(0, 0), b2, voffB); PG8_STAGE(PG8_SB(0, 1), b2 + hstepB, voffB); PG8_STAGE(PG8_SA(0, 0), a2, voffA);
;             PG8_WAIT_V(8); PG8_WAIT_L(0); PG8_BAR; PG8_MMA(1, 0, At, B0); PG8_MMA(1, 1, At, B1); PG8_BAR; PG8_SCHED;
;             PG8_LDB(B0, 1, 0); PG8_LDB(B1, 1, 1); PG8_SCHED; PG8_LDA(At, 1, 0); PG8_STAGE(PG8_SA(0, 1), a2 + hstepA, voffA);
;             PG8_WAIT_V(8); PG8_WAIT_L(0); PG8_BAR; PG8_MMA(0, 0, At, B0); PG8_MMA(0, 1, At, B1); PG8_BAR; PG8_SCHED;
.LBB0_1458:
	s_waitcnt lgkmcnt(0)
	ds_read_b128 v[0:3], v201
	ds_read_b128 v[4:7], v201 offset:1024
	ds_read_b128 v[8:11], v201 offset:2048
	ds_read_b128 v[12:15], v201 offset:3072
	ds_read_b128 v[16:19], v202
	ds_read_b128 v[20:23], v202 offset:1024
	ds_read_b128 v[104:107], v202 offset:2048
	ds_read_b128 v[116:119], v202 offset:3072
	s_add_u32 s14, s12, 0x100
	s_addc_u32 s15, s13, 0
	s_cmp_eq_u32 s74, 40
	s_cselect_b32 s51, s6, s15
	s_cselect_b32 s50, s69, s14
	s_cselect_b32 s49, s70, s73
	s_cselect_b32 s48, s71, s72
	v_lshl_add_u64 v[218:219], s[12:13], 0, v[176:177]
	s_add_i32 m0, s52, 0xc000
	ds_read_b128 v[124:127], v203
	ds_read_b128 v[132:135], v203 offset:1024
	ds_read_b128 v[184:187], v203 offset:2048
	ds_read_b128 v[188:191], v203 offset:3072
	ds_read_b128 v[192:195], v203 offset:4096
	ds_read_b128 v[206:209], v203 offset:5120
	ds_read_b128 v[210:213], v203 offset:6144
	ds_read_b128 v[214:217], v203 offset:7168
	global_load_lds_dwordx4 v[218:219], off
	v_lshl_add_u64 v[218:219], s[12:13], 0, v[178:179]
	s_add_i32 m0, s52, 0xe000
	s_nop 0
	global_load_lds_dwordx4 v[218:219], off
	s_lshl_b32 s98, s68, 20
	s_lshl_b32 s99, s67, 10
	s_add_u32 s98, s98, s99
	s_and_b32 s99, s74, 30
	s_lshl_b32 s99, s99, 12
	s_add_u32 s98, s98, s99
	s_add_u32 s98, s98, s4
	s_addc_u32 s99, s5, 0
	v_lshl_add_u64 v[236:237], s[98:99], 0, v[234:235]
	global_load_dword v238, v[236:237], off
	s_waitcnt vmcnt(9)
	s_waitcnt lgkmcnt(0)
	s_barrier
	s_setprio 1
	s_waitcnt lgkmcnt(0)
	v_mfma_f32_16x16x32_bf16 v[28:31], v[0:3], v[124:127], v[28:31]
	v_mfma_f32_16x16x32_bf16 v[24:27], v[8:11], v[124:127], v[24:27]
	v_mfma_f32_16x16x32_bf16 v[44:47], v[0:3], v[184:187], v[44:47]
	v_mfma_f32_16x16x32_bf16 v[40:43], v[8:11], v[184:187], v[40:43]
	v_mfma_f32_16x16x32_bf16 v[156:159], v[0:3], v[192:195], v[156:159]
	v_mfma_f32_16x16x32_bf16 v[152:155], v[8:11], v[192:195], v[152:155]
	v_mfma_f32_16x16x32_bf16 v[140:143], v[0:3], v[210:213], v[140:143]
	v_mfma_f32_16x16x32_bf16 v[136:139], v[8:11], v[210:213], v[136:139]
	v_mfma_f32_16x16x32_bf16 v[28:31], v[4:7], v[132:135], v[28:31]
	v_mfma_f32_16x16x32_bf16 v[24:27], v[12:15], v[132:135], v[24:27]
	v_mfma_f32_16x16x32_bf16 v[44:47], v[4:7], v[188:191], v[44:47]
	v_mfma_f32_16x16x32_bf16 v[40:43], v[12:15], v[188:191], v[40:43]
	v_mfma_f32_16x16x32_bf16 v[156:159], v[4:7], v[206:209], v[156:159]
	v_mfma_f32_16x16x32_bf16 v[152:155], v[12:15], v[206:209], v[152:155]
	v_mfma_f32_16x16x32_bf16 v[140:143], v[4:7], v[214:217], v[140:143]
	v_mfma_f32_16x16x32_bf16 v[136:139], v[12:15], v[214:217], v[136:139]
	s_setprio 0
	s_setprio 1
	v_mfma_f32_16x16x32_bf16 v[36:39], v[16:19], v[124:127], v[36:39]
	v_mfma_f32_16x16x32_bf16 v[32:35], v[104:107], v[124:127], v[32:35]
	v_mfma_f32_16x16x32_bf16 v[148:151], v[16:19], v[192:195], v[148:151]
	v_mfma_f32_16x16x32_bf16 v[144:147], v[104:107], v[192:195], v[144:147]
	v_mfma_f32_16x16x32_bf16 v[128:131], v[16:19], v[210:213], v[128:131]
	v_mfma_f32_16x16x32_bf16 v[120:123], v[104:107], v[210:213], v[120:123]
	v_mfma_f32_16x16x32_bf16 v[36:39], v[20:23], v[132:135], v[36:39]
	v_mfma_f32_16x16x32_bf16 v[32:35], v[116:119], v[132:135], v[32:35]
	v_mfma_f32_16x16x32_bf16 v[124:127], v[16:19], v[184:187], v[164:167]
	v_mfma_f32_16x16x32_bf16 v[132:135], v[104:107], v[184:187], v[160:163]
	v_mfma_f32_16x16x32_bf16 v[148:151], v[20:23], v[206:209], v[148:151]
	v_mfma_f32_16x16x32_bf16 v[144:147], v[116:119], v[206:209], v[144:147]
	v_mfma_f32_16x16x32_bf16 v[128:131], v[20:23], v[214:217], v[128:131]
	v_mfma_f32_16x16x32_bf16 v[120:123], v[116:119], v[214:217], v[120:123]
	v_mfma_f32_16x16x32_bf16 v[124:127], v[20:23], v[188:191], v[124:127]
	v_mfma_f32_16x16x32_bf16 v[132:135], v[116:119], v[188:191], v[132:135]
	s_setprio 0
	s_barrier
	s_add_i32 s12, s62, s33
	v_lshl_add_u64 v[226:227], s[48:49], 0, v[170:171]
	s_mov_b32 m0, s12
	ds_read_b128 v[160:163], v203 offset:16384
	ds_read_b128 v[164:167], v203 offset:17408
	ds_read_b128 v[184:187], v203 offset:18432
	ds_read_b128 v[188:191], v203 offset:19456
	ds_read_b128 v[192:195], v203 offset:20480
	ds_read_b128 v[206:209], v203 offset:21504
	ds_read_b128 v[210:213], v203 offset:22528
	ds_read_b128 v[214:217], v203 offset:23552
	global_load_lds_dwordx4 v[226:227], off
	s_add_i32 m0, s12, 0x2000
	s_add_u32 s12, s48, 0xb0000
	v_lshl_add_u64 v[228:229], s[48:49], 0, v[174:175]
	s_addc_u32 s13, s49, 0
	s_add_i32 s75, s63, s33
	global_load_lds_dwordx4 v[228:229], off
	v_lshl_add_u64 v[218:219], s[12:13], 0, v[170:171]
	s_mov_b32 m0, s75
	v_lshl_add_u64 v[230:231], s[50:51], 0, v[168:169]
	global_load_lds_dwordx4 v[218:219], off
	v_lshl_add_u64 v[218:219], s[12:13], 0, v[174:175]
	s_add_i32 m0, s75, 0x2000
	v_lshl_add_u64 v[232:233], s[50:51], 0, v[172:173]
	global_load_lds_dwordx4 v[218:219], off
	s_mov_b32 m0, s52
	s_nop 0
	global_load_lds_dwordx4 v[230:231], off
	s_mov_b32 m0, s53
	s_nop 0
	global_load_lds_dwordx4 v[232:233], off
	s_waitcnt vmcnt(9)
	s_waitcnt lgkmcnt(0)
	s_barrier
; #define PG8_STAGE(bufoff, gbase, voff) do { _Pragma("unroll") for (int _i = 0; _i < 2; ++_i) \
;         __builtin_amdgcn_global_load_lds((const unsigned*)((const char*)(gbase) + (voff)[_i]), (PG8_LAS unsigned*)(lds + (bufoff) + ldsw + _i * 8192), 16, 0, 0); } while (0)
; #define PG8_LDA(dst, b, h) do { _Pragma("unroll") for (int m = 0; m < 4; ++m) _Pragma("unroll") for (int k = 0; k < 2; ++k) dst[m][k] = *(const PG8_LAS bf16x8*)(lds + PG8_SA(b, h) + aoff + m * 2048 + k * 1024); } while (0)
; #define PG8_LDB(dst, b, h) do { _Pragma("unroll") for (int n = 0; n < 2; ++n) _Pragma("unroll") for (int k = 0; k < 2; ++k) dst[n][k] = *(const PG8_LAS bf16x8*)(lds + PG8_SB(b, h) + boff + n * 2048 + k * 1024); } while (0)
; #define PG8_MMA(ai, bj, At, Bt) do { __builtin_amdgcn_s_setprio(1); _Pragma("unroll") for (int m = 0; m < 4; ++m) _Pragma("unroll") for (int n = 0; n < 2; ++n) _Pragma("unroll") for (int k = 0; k < 2; ++k) \
;         acc[ai][bj][m][n] = __builtin_amdgcn_mfma_f32_16x16x32_bf16(Bt[n][k], At[m][k], acc[ai][bj][m][n], 0, 0, 0); __builtin_amdgcn_s_setprio(0); } while (0)
; #define PG8_WAIT_V(n) asm volatile("s_waitcnt vmcnt(" #n ")" ::: "memory")
; #define PG8_WAIT_L(n) asm volatile("s_waitcnt lgkmcnt(" #n ")" ::: "memory")
; #define PG8_BAR __builtin_amdgcn_s_barrier()
; #define PG8_SCHED __builtin_amdgcn_sched_barrier(0)
; template <class Epi, class Sched>
; __device__ __forceinline__ void gemm_phase(PG8_LAS unsigned char* lds, const Gemm g, const Sched& S, const Epi& E) {
;     ...
;             PG8_WAIT_V(8); PG8_WAIT_L(0); PG8_BAR; PG8_MMA(0, 0, At, B0); PG8_MMA(0, 1, At, B1); PG8_BAR; PG8_SCHED;
;             PG8_LDA(At, 0, 1); PG8_STAGE(PG8_SB(0, 0), b2, voffB); PG8_STAGE(PG8_SB(0, 1), b2 + hstepB, voffB); PG8_STAGE(PG8_SA(0, 0), a2, voffA);
;             PG8_WAIT_V(8); PG8_WAIT_L(0); PG8_BAR; PG8_MMA(1, 0, At, B0); PG8_MMA(1, 1, At, B1); PG8_BAR; PG8_SCHED;
;             PG8_LDB(B0, 1, 0); PG8_LDB(B1, 1, 1); PG8_SCHED; PG8_LDA(At, 1, 0); PG8_STAGE(PG8_SA(0, 1), a2 + hstepA, voffA);
;             PG8_WAIT_V(8); PG8_WAIT_L(0); PG8_BAR; PG8_MMA(0, 0, At, B0); PG8_MMA(0, 1, At, B1); PG8_BAR; PG8_SCHED;
;             PG8_LDA(At, 1, 1); PG8_STAGE(PG8_SB(1, 0), b3, voffB); PG8_STAGE(PG8_SB(1, 1), b3 + hstepB, voffB); PG8_STAGE(PG8_SA(1, 0), a3, voffA);
	s_setprio 1
	s_waitcnt lgkmcnt(0)
	v_mfma_f32_16x16x32_bf16 v[112:115], v[0:3], v[160:163], v[112:115]
	v_mfma_f32_16x16x32_bf16 v[108:111], v[8:11], v[160:163], v[108:111]
	v_mfma_f32_16x16x32_bf16 v[92:95], v[0:3], v[184:187], v[92:95]
	v_mfma_f32_16x16x32_bf16 v[88:91], v[8:11], v[184:187], v[88:91]
	v_mfma_f32_16x16x32_bf16 v[76:79], v[0:3], v[192:195], v[76:79]
	v_mfma_f32_16x16x32_bf16 v[72:75], v[8:11], v[192:195], v[72:75]
	v_mfma_f32_16x16x32_bf16 v[0:3], v[0:3], v[210:213], v[60:63]
	v_mfma_f32_16x16x32_bf16 v[112:115], v[4:7], v[164:167], v[112:115]
	v_mfma_f32_16x16x32_bf16 v[108:111], v[12:15], v[164:167], v[108:111]
	v_mfma_f32_16x16x32_bf16 v[92:95], v[4:7], v[188:191], v[92:95]
	v_mfma_f32_16x16x32_bf16 v[88:91], v[12:15], v[188:191], v[88:91]
	v_mfma_f32_16x16x32_bf16 v[76:79], v[4:7], v[206:209], v[76:79]
	v_mfma_f32_16x16x32_bf16 v[72:75], v[12:15], v[206:209], v[72:75]
	v_mfma_f32_16x16x32_bf16 v[0:3], v[4:7], v[214:217], v[0:3]
	v_mfma_f32_16x16x32_bf16 v[4:7], v[8:11], v[210:213], v[56:59]
	v_mfma_f32_16x16x32_bf16 v[4:7], v[12:15], v[214:217], v[4:7]
	s_setprio 0
	s_setprio 1
	v_mfma_f32_16x16x32_bf16 v[56:59], v[16:19], v[184:187], v[84:87]
	v_mfma_f32_16x16x32_bf16 v[84:87], v[20:23], v[188:191], v[56:59]
	v_mfma_f32_16x16x32_bf16 v[56:59], v[104:107], v[184:187], v[80:83]
	v_mfma_f32_16x16x32_bf16 v[80:83], v[116:119], v[188:191], v[56:59]
	v_mfma_f32_16x16x32_bf16 v[56:59], v[16:19], v[192:195], v[68:71]
	v_mfma_f32_16x16x32_bf16 v[8:11], v[16:19], v[160:163], v[100:103]
	v_mfma_f32_16x16x32_bf16 v[68:71], v[20:23], v[206:209], v[56:59]
	v_mfma_f32_16x16x32_bf16 v[56:59], v[104:107], v[192:195], v[64:67]
	v_mfma_f32_16x16x32_bf16 v[16:19], v[16:19], v[210:213], v[52:55]
	v_mfma_f32_16x16x32_bf16 v[8:11], v[20:23], v[164:167], v[8:11]
	v_mfma_f32_16x16x32_bf16 v[12:15], v[104:107], v[160:163], v[96:99]
	v_mfma_f32_16x16x32_bf16 v[64:67], v[116:119], v[206:209], v[56:59]
	v_mfma_f32_16x16x32_bf16 v[16:19], v[20:23], v[214:217], v[16:19]
	v_mfma_f32_16x16x32_bf16 v[20:23], v[104:107], v[210:213], v[48:51]
	v_mfma_f32_16x16x32_bf16 v[12:15], v[116:119], v[164:167], v[12:15]
	v_mfma_f32_16x16x32_bf16 v[20:23], v[116:119], v[214:217], v[20:23]
	s_setprio 0
	s_barrier
	s_add_i32 s75, 0, 0x18000
	v_add_u32_e32 v60, s75, v197
	s_add_i32 s76, 0, 0x1c000
	ds_read_b128 v[48:51], v60
	ds_read_b128 v[52:55], v60 offset:1024
	ds_read_b128 v[56:59], v60 offset:2048
	ds_read_b128 v[96:99], v60 offset:3072
	v_add_u32_e32 v60, s76, v197
	ds_read_b128 v[104:107], v60
	ds_read_b128 v[116:119], v60 offset:1024
	ds_read_b128 v[184:187], v60 offset:2048
	ds_read_b128 v[188:191], v60 offset:3072
	s_add_u32 s12, s50, 0xb0000
	s_addc_u32 s13, s51, 0
	s_mov_b32 m0, s54
	v_lshl_add_u64 v[164:165], s[12:13], 0, v[168:169]
	ds_read_b128 v[60:63], v203 offset:32768
	ds_read_b128 v[100:103], v203 offset:33792
	ds_read_b128 v[160:163], v203 offset:34816
	ds_read_b128 v[192:195], v203 offset:35840
	ds_read_b128 v[206:209], v203 offset:36864
	ds_read_b128 v[210:213], v203 offset:37888
	ds_read_b128 v[214:217], v203 offset:38912
	ds_read_b128 v[218:221], v203 offset:39936
	global_load_lds_dwordx4 v[164:165], off
	v_lshl_add_u64 v[164:165], s[12:13], 0, v[172:173]
	s_mov_b32 m0, s55
	s_nop 0
	global_load_lds_dwordx4 v[164:165], off
	s_waitcnt vmcnt(9)
	s_waitcnt lgkmcnt(0)
	s_barrier
	s_setprio 1
	s_waitcnt lgkmcnt(0)
	v_mfma_f32_16x16x32_bf16 v[28:31], v[48:51], v[60:63], v[28:31]
	v_mfma_f32_16x16x32_bf16 v[24:27], v[56:59], v[60:63], v[24:27]
	v_mfma_f32_16x16x32_bf16 v[44:47], v[48:51], v[160:163], v[44:47]
	v_mfma_f32_16x16x32_bf16 v[40:43], v[56:59], v[160:163], v[40:43]
	v_mfma_f32_16x16x32_bf16 v[156:159], v[48:51], v[206:209], v[156:159]
	v_mfma_f32_16x16x32_bf16 v[152:155], v[56:59], v[206:209], v[152:155]
	v_mfma_f32_16x16x32_bf16 v[140:143], v[48:51], v[214:217], v[140:143]
	v_mfma_f32_16x16x32_bf16 v[136:139], v[56:59], v[214:217], v[136:139]
	v_mfma_f32_16x16x32_bf16 v[28:31], v[52:55], v[100:103], v[28:31]
	v_mfma_f32_16x16x32_bf16 v[24:27], v[96:99], v[100:103], v[24:27]
	v_mfma_f32_16x16x32_bf16 v[44:47], v[52:55], v[192:195], v[44:47]
	v_mfma_f32_16x16x32_bf16 v[40:43], v[96:99], v[192:195], v[40:43]
	v_mfma_f32_16x16x32_bf16 v[156:159], v[52:55], v[210:213], v[156:159]
	v_mfma_f32_16x16x32_bf16 v[152:155], v[96:99], v[210:213], v[152:155]
	v_mfma_f32_16x16x32_bf16 v[140:143], v[52:55], v[218:221], v[140:143]
	v_mfma_f32_16x16x32_bf16 v[136:139], v[96:99], v[218:221], v[136:139]
	s_setprio 0
	s_setprio 1
	v_mfma_f32_16x16x32_bf16 v[36:39], v[104:107], v[60:63], v[36:39]
	v_mfma_f32_16x16x32_bf16 v[32:35], v[184:187], v[60:63], v[32:35]
	v_mfma_f32_16x16x32_bf16 v[60:63], v[104:107], v[160:163], v[124:127]
	v_mfma_f32_16x16x32_bf16 v[164:167], v[116:119], v[192:195], v[60:63]
	v_mfma_f32_16x16x32_bf16 v[60:63], v[184:187], v[160:163], v[132:135]
	v_mfma_f32_16x16x32_bf16 v[160:163], v[188:191], v[192:195], v[60:63]
	v_mfma_f32_16x16x32_bf16 v[60:63], v[104:107], v[206:209], v[148:151]
	v_mfma_f32_16x16x32_bf16 v[148:151], v[116:119], v[210:213], v[60:63]
	v_mfma_f32_16x16x32_bf16 v[60:63], v[184:187], v[206:209], v[144:147]
	v_mfma_f32_16x16x32_bf16 v[144:147], v[188:191], v[210:213], v[60:63]
	v_mfma_f32_16x16x32_bf16 v[60:63], v[104:107], v[214:217], v[128:131]
	v_mfma_f32_16x16x32_bf16 v[128:131], v[116:119], v[218:221], v[60:63]
	v_mfma_f32_16x16x32_bf16 v[60:63], v[184:187], v[214:217], v[120:123]
	v_mfma_f32_16x16x32_bf16 v[36:39], v[116:119], v[100:103], v[36:39]
	v_mfma_f32_16x16x32_bf16 v[32:35], v[188:191], v[100:103], v[32:35]
	v_mfma_f32_16x16x32_bf16 v[120:123], v[188:191], v[218:221], v[60:63]
	s_setprio 0
	s_barrier
; #define PG8_STAGE(bufoff, gbase, voff) do { _Pragma("unroll") for (int _i = 0; _i < 2; ++_i) \
;         __builtin_amdgcn_global_load_lds((const unsigned*)((const char*)(gbase) + (voff)[_i]), (PG8_LAS unsigned*)(lds + (bufoff) + ldsw + _i * 8192), 16, 0, 0); } while (0)
; #define PG8_LDA(dst, b, h) do { _Pragma("unroll") for (int m = 0; m < 4; ++m) _Pragma("unroll") for (int k = 0; k < 2; ++k) dst[m][k] = *(const PG8_LAS bf16x8*)(lds + PG8_SA(b, h) + aoff + m * 2048 + k * 1024); } while (0)
; #define PG8_MMA(ai, bj, At, Bt) do { __builtin_amdgcn_s_setprio(1); _Pragma("unroll") for (int m = 0; m < 4; ++m) _Pragma("unroll") for (int n = 0; n < 2; ++n) _Pragma("unroll") for (int k = 0; k < 2; ++k) \
;         acc[ai][bj][m][n] = __builtin_amdgcn_mfma_f32_16x16x32_bf16(Bt[n][k], At[m][k], acc[ai][bj][m][n], 0, 0, 0); __builtin_amdgcn_s_setprio(0); } while (0)
; #define PG8_WAIT_V(n) asm volatile("s_waitcnt vmcnt(" #n ")" ::: "memory")
; #define PG8_WAIT_L(n) asm volatile("s_waitcnt lgkmcnt(" #n ")" ::: "memory")
; #define PG8_BAR __builtin_amdgcn_s_barrier()
; #define PG8_SCHED __builtin_amdgcn_sched_barrier(0)
; template <class Epi, class Sched>
; __device__ __forceinline__ void gemm_phase(PG8_LAS unsigned char* lds, const Gemm g, const Sched& S, const Epi& E) {
;     ...
;             PG8_WAIT_V(8); PG8_WAIT_L(0); PG8_BAR; PG8_MMA(0, 0, At, B0); PG8_MMA(0, 1, At, B1); PG8_BAR; PG8_SCHED;
;             PG8_LDA(At, 1, 1); PG8_STAGE(PG8_SB(1, 0), b3, voffB); PG8_STAGE(PG8_SB(1, 1), b3 + hstepB, voffB); PG8_STAGE(PG8_SA(1, 0), a3, voffA);
;             PG8_WAIT_V(8); PG8_WAIT_L(0); PG8_BAR; PG8_MMA(1, 0, At, B0); PG8_MMA(1, 1, At, B1); PG8_BAR; PG8_SCHED;
;         }
	s_add_i32 s12, s75, s33
	s_nop 1
	v_lshl_add_u64 v[60:61], v[226:227], 0, s[30:31]
	s_mov_b32 m0, s12
	ds_read_b128 v[124:127], v203 offset:49152
	ds_read_b128 v[132:135], v203 offset:50176
	ds_read_b128 v[192:195], v203 offset:51200
	ds_read_b128 v[206:209], v203 offset:52224
	ds_read_b128 v[210:213], v203 offset:53248
	ds_read_b128 v[214:217], v203 offset:54272
	ds_read_b128 v[218:221], v203 offset:55296
	ds_read_b128 v[222:225], v203 offset:56320
	global_load_lds_dwordx4 v[60:61], off
	s_add_i32 m0, s12, 0x2000
	s_add_u32 s12, s48, 0xb0080
	v_lshl_add_u64 v[60:61], v[228:229], 0, s[30:31]
	s_addc_u32 s13, s49, 0
	s_add_i32 s48, s76, s33
	global_load_lds_dwordx4 v[60:61], off
	v_lshl_add_u64 v[60:61], s[12:13], 0, v[170:171]
	s_mov_b32 m0, s48
	s_nop 0
	global_load_lds_dwordx4 v[60:61], off
	v_lshl_add_u64 v[60:61], s[12:13], 0, v[174:175]
	s_add_i32 m0, s48, 0x2000
	s_nop 0
	global_load_lds_dwordx4 v[60:61], off
	v_lshl_add_u64 v[60:61], v[230:231], 0, s[30:31]
	s_mov_b32 m0, s57
	s_nop 0
	global_load_lds_dwordx4 v[60:61], off
	v_lshl_add_u64 v[60:61], v[232:233], 0, s[30:31]
	s_mov_b32 m0, s58
	s_nop 0
	global_load_lds_dwordx4 v[60:61], off
	s_waitcnt vmcnt(8)
	s_waitcnt lgkmcnt(0)
	s_barrier
	s_setprio 1
	s_waitcnt lgkmcnt(0)
	v_mfma_f32_16x16x32_bf16 v[60:63], v[48:51], v[124:127], v[112:115]
	v_mfma_f32_16x16x32_bf16 v[112:115], v[52:55], v[132:135], v[60:63]
	v_mfma_f32_16x16x32_bf16 v[60:63], v[56:59], v[124:127], v[108:111]
	v_mfma_f32_16x16x32_bf16 v[108:111], v[96:99], v[132:135], v[60:63]
	v_mfma_f32_16x16x32_bf16 v[60:63], v[48:51], v[192:195], v[92:95]
	v_mfma_f32_16x16x32_bf16 v[92:95], v[52:55], v[206:209], v[60:63]
	v_mfma_f32_16x16x32_bf16 v[60:63], v[56:59], v[192:195], v[88:91]
	v_mfma_f32_16x16x32_bf16 v[88:91], v[96:99], v[206:209], v[60:63]
	v_mfma_f32_16x16x32_bf16 v[60:63], v[48:51], v[210:213], v[76:79]
	v_mfma_f32_16x16x32_bf16 v[76:79], v[52:55], v[214:217], v[60:63]
	v_mfma_f32_16x16x32_bf16 v[60:63], v[56:59], v[210:213], v[72:75]
	v_mfma_f32_16x16x32_bf16 v[0:3], v[48:51], v[218:221], v[0:3]
	v_mfma_f32_16x16x32_bf16 v[72:75], v[96:99], v[214:217], v[60:63]
	v_mfma_f32_16x16x32_bf16 v[60:63], v[52:55], v[222:225], v[0:3]
	v_mfma_f32_16x16x32_bf16 v[0:3], v[56:59], v[218:221], v[4:7]
	v_mfma_f32_16x16x32_bf16 v[56:59], v[96:99], v[222:225], v[0:3]
	s_setprio 0
	s_setprio 1
	v_mfma_f32_16x16x32_bf16 v[0:3], v[104:107], v[124:127], v[8:11]
	v_mfma_f32_16x16x32_bf16 v[100:103], v[116:119], v[132:135], v[0:3]
	v_mfma_f32_16x16x32_bf16 v[0:3], v[184:187], v[124:127], v[12:15]
	v_mfma_f32_16x16x32_bf16 v[96:99], v[188:191], v[132:135], v[0:3]
	v_mfma_f32_16x16x32_bf16 v[0:3], v[104:107], v[192:195], v[84:87]
	v_mfma_f32_16x16x32_bf16 v[84:87], v[116:119], v[206:209], v[0:3]
	v_mfma_f32_16x16x32_bf16 v[0:3], v[184:187], v[192:195], v[80:83]
	v_mfma_f32_16x16x32_bf16 v[80:83], v[188:191], v[206:209], v[0:3]
	v_mfma_f32_16x16x32_bf16 v[0:3], v[104:107], v[210:213], v[68:71]
	v_mfma_f32_16x16x32_bf16 v[68:71], v[116:119], v[214:217], v[0:3]
	v_mfma_f32_16x16x32_bf16 v[0:3], v[184:187], v[210:213], v[64:67]
	v_mfma_f32_16x16x32_bf16 v[64:67], v[188:191], v[214:217], v[0:3]
	v_mfma_f32_16x16x32_bf16 v[0:3], v[104:107], v[218:221], v[16:19]
	v_mfma_f32_16x16x32_bf16 v[52:55], v[116:119], v[222:225], v[0:3]
	v_mfma_f32_16x16x32_bf16 v[0:3], v[184:187], v[218:221], v[20:23]
	v_mfma_f32_16x16x32_bf16 v[48:51], v[188:191], v[222:225], v[0:3]
	s_setprio 0
	s_barrier
	s_add_i32 s74, s74, 2
	s_add_u32 s72, s72, 0x100
	s_addc_u32 s73, s73, 0
	s_cmp_gt_u32 s74, 41
	s_mov_b64 s[12:13], s[14:15]
	s_cbranch_scc0 .LBB0_1458
	s_and_b64 vcc, exec, s[34:35]
	s_cbranch_vccz .LBB0_1461
	s_barrier
